# attention epilogue: one wait for the gate loads, no counted waits that serialise on the epilogue's own store acks
# speedup vs baseline: 1.0123x; 1.0043x over previous
; __device__ __forceinline__ unsigned pack2(float a, float b) { unsigned r; asm volatile("v_cvt_pk_bf16_f32 %0, %1, %2" : "=v"(r) : "v"(a), "v"(b)); return r; }
; __device__ __forceinline__ void item_attn(const Params& p, int l, int aidx) {
;     ...
;   {
;     uint2 gz[2][4];
; #pragma unroll
;     for (int n = 0; n < 2; ++n) {
;       int row = 32 * wid + 16 * n + fr; if (row >= nq) row = nq - 1;
; #pragma unroll
;       for (int md = 0; md < 4; ++md) gz[n][md] = *reinterpret_cast<const uint2*>(p.gzc + (tokq0 + row) * 512 + hd * 64 + md * 16 + fq * 4);
;     }
; #pragma unroll
;     for (int n = 0; n < 2; ++n) {
;       const int row = 32 * wid + 16 * n + fr;
; #pragma unroll
;       for (int md = 0; md < 4; ++md) {
;         const uint2 g2 = gz[n][md];
;         float g0 = __uint_as_float(g2.x << 16), g1 = __uint_as_float(g2.x & 0xffff0000u);
;         float g2f = __uint_as_float(g2.y << 16), g3 = __uint_as_float(g2.y & 0xffff0000u);
;         uint2 o2; o2.x = pack2(oacc[md][n][0] * g0, oacc[md][n][1] * g1); o2.y = pack2(oacc[md][n][2] * g2f, oacc[md][n][3] * g3);
;         if (row < nq) *reinterpret_cast<uint2*>(p.sq + (tokq0 + row) * 512 + hd * 64 + md * 16 + fq * 4) = o2;
;       }
;     }
;   }
.LBB0_773:
	s_add_i32 s2, s47, -1
	v_readlane_b32 s12, v247, 7
	v_readlane_b32 s18, v247, 13
	v_min_i32_e32 v2, s2, v84
	v_readlane_b32 s19, v247, 14
	s_add_u32 s0, s18, s44
	v_ashrrev_i32_e32 v3, 31, v2
	s_addc_u32 s1, s19, s45
	v_lshlrev_b32_e32 v190, 1, v114
	v_lshl_add_u64 v[2:3], s[34:35], 0, v[2:3]
	v_lshl_add_u64 v[0:1], s[0:1], 0, v[190:191]
	v_lshlrev_b64 v[2:3], 10, v[2:3]
	v_lshl_add_u64 v[2:3], v[0:1], 0, v[2:3]
	global_load_dwordx2 v[10:11], v[2:3], off
	global_load_dwordx2 v[14:15], v[2:3], off offset:32
	global_load_dwordx2 v[12:13], v[2:3], off offset:64
	global_load_dwordx2 v[8:9], v[2:3], off offset:96
	v_min_i32_e32 v2, s2, v86
	v_ashrrev_i32_e32 v3, 31, v2
	v_lshl_add_u64 v[2:3], s[34:35], 0, v[2:3]
	v_lshlrev_b64 v[2:3], 10, v[2:3]
	v_lshl_add_u64 v[0:1], v[0:1], 0, v[2:3]
	global_load_dwordx2 v[6:7], v[0:1], off
	global_load_dwordx2 v[4:5], v[0:1], off offset:32
	global_load_dwordx2 v[2:3], v[0:1], off offset:64
	s_nop 0
	global_load_dwordx2 v[0:1], v[0:1], off offset:96
	v_readlane_b32 s16, v247, 11
	v_readlane_b32 s17, v247, 12
	v_readlane_b32 s13, v247, 8
	v_readlane_b32 s14, v247, 9
	s_waitcnt vmcnt(0)
	v_lshl_add_u64 v[18:19], s[16:17], 0, v[82:83]
	v_readlane_b32 s15, v247, 10
	v_readlane_b32 s20, v247, 15
	v_readlane_b32 s21, v247, 16
	v_readlane_b32 s22, v247, 17
	v_readlane_b32 s23, v247, 18
	v_readlane_b32 s24, v247, 19
	v_readlane_b32 s25, v247, 20
	v_readlane_b32 s26, v247, 21
	v_readlane_b32 s27, v247, 22
	v_lshlrev_b32_e32 v16, 16, v10
	v_and_b32_e32 v10, 0xffff0000, v10
	v_lshlrev_b32_e32 v17, 16, v11
	v_and_b32_e32 v11, 0xffff0000, v11
	v_mul_f32_e32 v16, v60, v16
	v_mul_f32_e32 v10, v61, v10
	v_mul_f32_e32 v17, v62, v17
	v_mul_f32_e32 v11, v63, v11
	v_cvt_pk_bf16_f32 v16, v16, v10
	v_cvt_pk_bf16_f32 v17, v17, v11
	v_lshl_add_u64 v[10:11], s[28:29], 1, v[18:19]
	s_and_saveexec_b64 s[0:1], s[8:9]
	s_cbranch_execz .LBB0_775
	v_lshl_add_u64 v[18:19], v[10:11], 0, v[190:191]
	global_store_dwordx2 v[18:19], v[16:17], off
